# v39 + G1 unit loop: redundant vmcnt(0) inside the accumulator-zeroing run removed
# baseline (speedup 1.0000x reference)
.LBB0_393:
	s_ashr_i32 s19, s18, 31
	s_lshl_b64 s[0:1], s[18:19], 20
	s_add_u32 s20, s42, s0
	s_addc_u32 s21, s43, s1
	s_and_b64 s[0:1], s[4:5], exec
	s_cselect_b32 s7, s21, s25
	s_cselect_b32 s19, s20, s24
	s_ashr_i32 s17, s16, 31
	s_lshl_b64 s[0:1], s[16:17], 20
	s_add_u32 s22, s30, s0
	s_addc_u32 s23, s31, s1
	s_and_b64 s[0:1], s[4:5], exec
	s_cselect_b32 s17, s23, s27
	s_cselect_b32 s49, s22, s26
	s_add_u32 s24, s24, 0x80080
	s_addc_u32 s25, s25, 0
	s_add_u32 s58, s26, 0x100
	v_mov_b32_e32 v2, 0
	s_addc_u32 s59, s27, 0
	s_mov_b32 s60, -2
	v_mov_b32_e32 v3, v2
	s_waitcnt lgkmcnt(0)
	v_pk_mov_b32 v[4:5], v[2:3], v[2:3] op_sel:[0,1]
	v_pk_mov_b32 v[6:7], v[2:3], v[2:3] op_sel:[0,1]
	v_pk_mov_b32 v[8:9], v[2:3], v[2:3] op_sel:[0,1]
	v_pk_mov_b32 v[18:19], v[2:3], v[2:3] op_sel:[0,1]
	v_pk_mov_b32 v[20:21], v[2:3], v[2:3] op_sel:[0,1]
	v_pk_mov_b32 v[22:23], v[2:3], v[2:3] op_sel:[0,1]
	v_pk_mov_b32 v[24:25], v[2:3], v[2:3] op_sel:[0,1]
	v_pk_mov_b32 v[34:35], v[2:3], v[2:3] op_sel:[0,1]
	v_pk_mov_b32 v[36:37], v[2:3], v[2:3] op_sel:[0,1]
	v_pk_mov_b32 v[38:39], v[2:3], v[2:3] op_sel:[0,1]
	v_pk_mov_b32 v[40:41], v[2:3], v[2:3] op_sel:[0,1]
	v_pk_mov_b32 v[50:51], v[2:3], v[2:3] op_sel:[0,1]
	v_pk_mov_b32 v[52:53], v[2:3], v[2:3] op_sel:[0,1]
	v_pk_mov_b32 v[54:55], v[2:3], v[2:3] op_sel:[0,1]
	v_pk_mov_b32 v[56:57], v[2:3], v[2:3] op_sel:[0,1]
	v_pk_mov_b32 v[10:11], v[2:3], v[2:3] op_sel:[0,1]
	v_pk_mov_b32 v[12:13], v[2:3], v[2:3] op_sel:[0,1]
	v_pk_mov_b32 v[14:15], v[2:3], v[2:3] op_sel:[0,1]
	v_pk_mov_b32 v[16:17], v[2:3], v[2:3] op_sel:[0,1]
	v_pk_mov_b32 v[26:27], v[2:3], v[2:3] op_sel:[0,1]
	v_pk_mov_b32 v[28:29], v[2:3], v[2:3] op_sel:[0,1]
	v_pk_mov_b32 v[30:31], v[2:3], v[2:3] op_sel:[0,1]
	v_pk_mov_b32 v[32:33], v[2:3], v[2:3] op_sel:[0,1]
	v_pk_mov_b32 v[42:43], v[2:3], v[2:3] op_sel:[0,1]
	v_pk_mov_b32 v[44:45], v[2:3], v[2:3] op_sel:[0,1]
	v_pk_mov_b32 v[46:47], v[2:3], v[2:3] op_sel:[0,1]
	v_pk_mov_b32 v[48:49], v[2:3], v[2:3] op_sel:[0,1]
	v_pk_mov_b32 v[58:59], v[2:3], v[2:3] op_sel:[0,1]
	v_pk_mov_b32 v[60:61], v[2:3], v[2:3] op_sel:[0,1]
	v_pk_mov_b32 v[62:63], v[2:3], v[2:3] op_sel:[0,1]
	v_pk_mov_b32 v[64:65], v[2:3], v[2:3] op_sel:[0,1]
	v_pk_mov_b32 v[66:67], v[2:3], v[2:3] op_sel:[0,1]
	v_pk_mov_b32 v[68:69], v[2:3], v[2:3] op_sel:[0,1]
	v_pk_mov_b32 v[70:71], v[2:3], v[2:3] op_sel:[0,1]
	v_pk_mov_b32 v[72:73], v[2:3], v[2:3] op_sel:[0,1]
	v_pk_mov_b32 v[82:83], v[2:3], v[2:3] op_sel:[0,1]
	v_pk_mov_b32 v[84:85], v[2:3], v[2:3] op_sel:[0,1]
	v_pk_mov_b32 v[86:87], v[2:3], v[2:3] op_sel:[0,1]
	v_pk_mov_b32 v[88:89], v[2:3], v[2:3] op_sel:[0,1]
	v_pk_mov_b32 v[98:99], v[2:3], v[2:3] op_sel:[0,1]
	v_pk_mov_b32 v[100:101], v[2:3], v[2:3] op_sel:[0,1]
	v_pk_mov_b32 v[102:103], v[2:3], v[2:3] op_sel:[0,1]
	v_pk_mov_b32 v[104:105], v[2:3], v[2:3] op_sel:[0,1]
	v_pk_mov_b32 v[114:115], v[2:3], v[2:3] op_sel:[0,1]
	v_pk_mov_b32 v[116:117], v[2:3], v[2:3] op_sel:[0,1]
	v_pk_mov_b32 v[118:119], v[2:3], v[2:3] op_sel:[0,1]
	v_pk_mov_b32 v[120:121], v[2:3], v[2:3] op_sel:[0,1]
	v_pk_mov_b32 v[74:75], v[2:3], v[2:3] op_sel:[0,1]
	v_pk_mov_b32 v[76:77], v[2:3], v[2:3] op_sel:[0,1]
	v_pk_mov_b32 v[78:79], v[2:3], v[2:3] op_sel:[0,1]
	v_pk_mov_b32 v[80:81], v[2:3], v[2:3] op_sel:[0,1]
	v_pk_mov_b32 v[90:91], v[2:3], v[2:3] op_sel:[0,1]
	v_pk_mov_b32 v[92:93], v[2:3], v[2:3] op_sel:[0,1]
	v_pk_mov_b32 v[94:95], v[2:3], v[2:3] op_sel:[0,1]
	v_pk_mov_b32 v[96:97], v[2:3], v[2:3] op_sel:[0,1]
	v_pk_mov_b32 v[106:107], v[2:3], v[2:3] op_sel:[0,1]
	v_pk_mov_b32 v[108:109], v[2:3], v[2:3] op_sel:[0,1]
	v_pk_mov_b32 v[110:111], v[2:3], v[2:3] op_sel:[0,1]
	v_pk_mov_b32 v[112:113], v[2:3], v[2:3] op_sel:[0,1]
	v_pk_mov_b32 v[122:123], v[2:3], v[2:3] op_sel:[0,1]
	v_pk_mov_b32 v[124:125], v[2:3], v[2:3] op_sel:[0,1]
	v_pk_mov_b32 v[126:127], v[2:3], v[2:3] op_sel:[0,1]
	v_pk_mov_b32 v[128:129], v[2:3], v[2:3] op_sel:[0,1]
